# speedup vs baseline: 1.0073x; 1.0022x over previous
; __device__ void attn_a_item(const Params& p, int layer, int b, int h, int q128, unsigned char* smem) {
;     ...
;     const bool young = __builtin_amdgcn_readfirstlane(tid_) >= 256;
;     if (young) __builtin_amdgcn_s_setprio(1);
.LBB0_264:
	v_readfirstlane_b32 s2, v189
	s_cmpk_lt_i32 s2, 0x100
	s_cbranch_scc1 .Lmy_noprio
	s_setprio 1
